# v28 + barrier followers poll the top generation word directly (skip the per-XCD generation hop), XCD generation bumps kept for the deferred waiters
# speedup vs baseline: 1.0026x; 1.0026x over previous
.LBB0_25:
	s_or_b64 exec, exec, s[10:11]
	v_cvt_f32_u32_e32 v5, v3
	s_waitcnt vmcnt(0)
	v_readfirstlane_b32 s8, v4
	v_sub_u32_e32 v4, 0, v3
	v_rcp_iflag_f32_e32 v5, v5
	v_add_u32_e32 v6, s8, v2
	v_mul_f32_e32 v5, 0x4f7ffffe, v5
	v_cvt_u32_f32_e32 v5, v5
	v_mul_lo_u32 v2, v4, v5
	v_mul_hi_u32 v2, v5, v2
	v_add_u32_e32 v2, v5, v2
	v_mul_hi_u32 v2, v6, v2
	v_mul_lo_u32 v4, v2, v3
	v_sub_u32_e32 v4, v6, v4
	v_add_u32_e32 v5, 1, v2
	v_sub_u32_e32 v7, v4, v3
	v_cmp_ge_u32_e32 vcc, v4, v3
	s_nop 1
	v_cndmask_b32_e32 v2, v2, v5, vcc
	v_cndmask_b32_e32 v4, v4, v7, vcc
	v_add_u32_e32 v5, 1, v2
	v_cmp_ge_u32_e32 vcc, v4, v3
	v_add_u32_e32 v4, 1, v6
	s_nop 0
	v_cndmask_b32_e32 v2, v2, v5, vcc
	v_mul_lo_u32 v5, v3, v2
	v_add_u32_e32 v3, v5, v3
	v_cmp_ne_u32_e32 vcc, v4, v3
	s_and_saveexec_b64 s[8:9], vcc
	s_xor_b64 s[8:9], exec, s[8:9]
	s_cbranch_execz .LBB0_39
	s_waitcnt lgkmcnt(0)
	buffer_inv sc1
	v_mov_b32_e32 v1, 0x3500
	global_load_dword v1, v1, s[92:93] sc1
	s_add_u32 s12, s92, 0x3500
	s_addc_u32 s13, s93, 0
	s_waitcnt vmcnt(0)
	v_cmp_eq_u32_e32 vcc, v1, v2
	s_and_saveexec_b64 s[10:11], vcc
	s_cbranch_execz .LBB0_38
	s_mov_b32 s24, 1
	s_mov_b64 s[14:15], 0
	v_mov_b32_e32 v1, 0
	s_branch .LBB0_29

.LBB0_167:
	s_or_b64 exec, exec, s[8:9]
	v_cvt_f32_u32_e32 v5, v3
	s_waitcnt vmcnt(0)
	v_readfirstlane_b32 s6, v4
	v_sub_u32_e32 v4, 0, v3
	v_rcp_iflag_f32_e32 v5, v5
	v_add_u32_e32 v6, s6, v2
	v_mul_f32_e32 v5, 0x4f7ffffe, v5
	v_cvt_u32_f32_e32 v5, v5
	v_mul_lo_u32 v2, v4, v5
	v_mul_hi_u32 v2, v5, v2
	v_add_u32_e32 v2, v5, v2
	v_mul_hi_u32 v2, v6, v2
	v_mul_lo_u32 v4, v2, v3
	v_sub_u32_e32 v4, v6, v4
	v_add_u32_e32 v5, 1, v2
	v_sub_u32_e32 v7, v4, v3
	v_cmp_ge_u32_e32 vcc, v4, v3
	s_nop 1
	v_cndmask_b32_e32 v2, v2, v5, vcc
	v_cndmask_b32_e32 v4, v4, v7, vcc
	v_add_u32_e32 v5, 1, v2
	v_cmp_ge_u32_e32 vcc, v4, v3
	v_add_u32_e32 v4, 1, v6
	s_nop 0
	v_cndmask_b32_e32 v2, v2, v5, vcc
	v_mul_lo_u32 v5, v3, v2
	v_add_u32_e32 v3, v5, v3
	v_cmp_ne_u32_e32 vcc, v4, v3
	s_and_saveexec_b64 s[6:7], vcc
	s_xor_b64 s[6:7], exec, s[6:7]
	s_cbranch_execz .LBB0_181
	s_waitcnt lgkmcnt(0)
	buffer_inv sc1
	v_mov_b32_e32 v1, 0x3500
	global_load_dword v1, v1, s[92:93] sc1
	s_add_u32 s10, s92, 0x3500
	s_addc_u32 s11, s93, 0
	s_waitcnt vmcnt(0)
	v_cmp_eq_u32_e32 vcc, v1, v2
	s_and_saveexec_b64 s[8:9], vcc
	s_cbranch_execz .LBB0_180
	s_mov_b32 s22, 1
	s_mov_b64 s[12:13], 0
	v_mov_b32_e32 v1, 0
	s_branch .LBB0_171

.LBB0_230:
	s_or_b64 exec, exec, s[6:7]
	v_cvt_f32_u32_e32 v5, v3
	s_waitcnt vmcnt(0)
	v_readfirstlane_b32 s4, v4
	v_sub_u32_e32 v4, 0, v3
	v_rcp_iflag_f32_e32 v5, v5
	v_add_u32_e32 v6, s4, v2
	v_mul_f32_e32 v5, 0x4f7ffffe, v5
	v_cvt_u32_f32_e32 v5, v5
	v_mul_lo_u32 v2, v4, v5
	v_mul_hi_u32 v2, v5, v2
	v_add_u32_e32 v2, v5, v2
	v_mul_hi_u32 v2, v6, v2
	v_mul_lo_u32 v4, v2, v3
	v_sub_u32_e32 v4, v6, v4
	v_add_u32_e32 v5, 1, v2
	v_sub_u32_e32 v7, v4, v3
	v_cmp_ge_u32_e32 vcc, v4, v3
	s_nop 1
	v_cndmask_b32_e32 v2, v2, v5, vcc
	v_cndmask_b32_e32 v4, v4, v7, vcc
	v_add_u32_e32 v5, 1, v2
	v_cmp_ge_u32_e32 vcc, v4, v3
	v_add_u32_e32 v4, 1, v6
	s_nop 0
	v_cndmask_b32_e32 v2, v2, v5, vcc
	v_mul_lo_u32 v5, v3, v2
	v_add_u32_e32 v3, v5, v3
	v_cmp_ne_u32_e32 vcc, v4, v3
	s_and_saveexec_b64 s[4:5], vcc
	s_xor_b64 s[4:5], exec, s[4:5]
	s_cbranch_execz .LBB0_244
	s_waitcnt lgkmcnt(0)
	buffer_inv sc1
	v_mov_b32_e32 v1, 0x3500
	global_load_dword v1, v1, s[92:93] sc1
	s_add_u32 s8, s92, 0x3500
	s_addc_u32 s9, s93, 0
	s_waitcnt vmcnt(0)
	v_cmp_eq_u32_e32 vcc, v1, v2
	s_and_saveexec_b64 s[6:7], vcc
	s_cbranch_execz .LBB0_243
	s_mov_b32 s20, 1
	s_mov_b64 s[10:11], 0
	v_mov_b32_e32 v1, 0
	s_branch .LBB0_234

.LBB0_412:
	s_or_b64 exec, exec, s[8:9]
	v_cvt_f32_u32_e32 v5, v3
	s_waitcnt vmcnt(0)
	v_readfirstlane_b32 s6, v4
	v_sub_u32_e32 v4, 0, v3
	v_rcp_iflag_f32_e32 v5, v5
	v_add_u32_e32 v6, s6, v1
	v_mul_f32_e32 v5, 0x4f7ffffe, v5
	v_cvt_u32_f32_e32 v5, v5
	v_mul_lo_u32 v1, v4, v5
	v_mul_hi_u32 v1, v5, v1
	v_add_u32_e32 v1, v5, v1
	v_mul_hi_u32 v1, v6, v1
	v_mul_lo_u32 v4, v1, v3
	v_sub_u32_e32 v4, v6, v4
	v_add_u32_e32 v5, 1, v1
	v_cmp_ge_u32_e32 vcc, v4, v3
	s_nop 1
	v_cndmask_b32_e32 v1, v1, v5, vcc
	v_sub_u32_e32 v5, v4, v3
	v_cndmask_b32_e32 v4, v4, v5, vcc
	v_add_u32_e32 v5, 1, v1
	v_cmp_ge_u32_e32 vcc, v4, v3
	v_add_u32_e32 v4, 1, v6
	s_nop 0
	v_cndmask_b32_e32 v1, v1, v5, vcc
	v_mul_lo_u32 v5, v3, v1
	v_add_u32_e32 v3, v5, v3
	v_cmp_ne_u32_e32 vcc, v4, v3
	s_and_saveexec_b64 s[6:7], vcc
	s_xor_b64 s[6:7], exec, s[6:7]
	s_cbranch_execz .LBB0_426
	s_waitcnt lgkmcnt(0)
	buffer_inv sc1
	v_mov_b32_e32 v2, 0x3500
	global_load_dword v2, v2, s[92:93] sc1
	s_add_u32 s10, s92, 0x3500
	s_addc_u32 s11, s93, 0
	s_waitcnt vmcnt(0)
	v_cmp_eq_u32_e32 vcc, v2, v1
	s_and_saveexec_b64 s[8:9], vcc
	s_cbranch_execz .LBB0_425
	s_mov_b32 s22, 1
	s_mov_b64 s[12:13], 0
	v_mov_b32_e32 v2, 0
	s_branch .LBB0_416

.LBB0_476:
	s_or_b64 exec, exec, s[8:9]
	v_cvt_f32_u32_e32 v5, v3
	s_waitcnt vmcnt(0)
	v_readfirstlane_b32 s6, v4
	v_sub_u32_e32 v4, 0, v3
	v_rcp_iflag_f32_e32 v5, v5
	v_add_u32_e32 v6, s6, v2
	v_mul_f32_e32 v5, 0x4f7ffffe, v5
	v_cvt_u32_f32_e32 v5, v5
	v_mul_lo_u32 v2, v4, v5
	v_mul_hi_u32 v2, v5, v2
	v_add_u32_e32 v2, v5, v2
	v_mul_hi_u32 v2, v6, v2
	v_mul_lo_u32 v4, v2, v3
	v_sub_u32_e32 v4, v6, v4
	v_add_u32_e32 v5, 1, v2
	v_cmp_ge_u32_e32 vcc, v4, v3
	s_nop 1
	v_cndmask_b32_e32 v2, v2, v5, vcc
	v_sub_u32_e32 v5, v4, v3
	v_cndmask_b32_e32 v4, v4, v5, vcc
	v_add_u32_e32 v5, 1, v2
	v_cmp_ge_u32_e32 vcc, v4, v3
	v_add_u32_e32 v4, 1, v6
	s_nop 0
	v_cndmask_b32_e32 v2, v2, v5, vcc
	v_mul_lo_u32 v5, v3, v2
	v_add_u32_e32 v3, v5, v3
	v_cmp_ne_u32_e32 vcc, v4, v3
	s_and_saveexec_b64 s[6:7], vcc
	s_xor_b64 s[6:7], exec, s[6:7]
	s_cbranch_execz .LBB0_490
	s_waitcnt lgkmcnt(0)
	buffer_inv sc1
	v_mov_b32_e32 v1, 0x3500
	global_load_dword v1, v1, s[92:93] sc1
	s_add_u32 s10, s92, 0x3500
	s_addc_u32 s11, s93, 0
	s_waitcnt vmcnt(0)
	v_cmp_eq_u32_e32 vcc, v1, v2
	s_and_saveexec_b64 s[8:9], vcc
	s_cbranch_execz .LBB0_489
	s_mov_b32 s22, 1
	s_mov_b64 s[12:13], 0
	v_mov_b32_e32 v1, 0
	s_branch .LBB0_480

.LBB0_600:
	s_or_b64 exec, exec, s[6:7]
	v_cvt_f32_u32_e32 v5, v3
	s_waitcnt vmcnt(0)
	v_readfirstlane_b32 s4, v4
	v_sub_u32_e32 v4, 0, v3
	v_rcp_iflag_f32_e32 v5, v5
	v_add_u32_e32 v6, s4, v2
	v_mul_f32_e32 v5, 0x4f7ffffe, v5
	v_cvt_u32_f32_e32 v5, v5
	v_mul_lo_u32 v2, v4, v5
	v_mul_hi_u32 v2, v5, v2
	v_add_u32_e32 v2, v5, v2
	v_mul_hi_u32 v2, v6, v2
	v_mul_lo_u32 v4, v2, v3
	v_sub_u32_e32 v4, v6, v4
	v_add_u32_e32 v5, 1, v2
	v_cmp_ge_u32_e32 vcc, v4, v3
	s_nop 1
	v_cndmask_b32_e32 v2, v2, v5, vcc
	v_sub_u32_e32 v5, v4, v3
	v_cndmask_b32_e32 v4, v4, v5, vcc
	v_add_u32_e32 v5, 1, v2
	v_cmp_ge_u32_e32 vcc, v4, v3
	v_add_u32_e32 v4, 1, v6
	s_nop 0
	v_cndmask_b32_e32 v2, v2, v5, vcc
	v_mul_lo_u32 v5, v3, v2
	v_add_u32_e32 v3, v5, v3
	v_cmp_ne_u32_e32 vcc, v4, v3
	s_and_saveexec_b64 s[4:5], vcc
	s_xor_b64 s[4:5], exec, s[4:5]
	s_cbranch_execz .LBB0_614
	s_waitcnt lgkmcnt(0)
	buffer_inv sc1
	v_mov_b32_e32 v1, 0x3500
	global_load_dword v1, v1, s[92:93] sc1
	s_add_u32 s8, s92, 0x3500
	s_addc_u32 s9, s93, 0
	s_waitcnt vmcnt(0)
	v_cmp_eq_u32_e32 vcc, v1, v2
	s_and_saveexec_b64 s[6:7], vcc
	s_cbranch_execz .LBB0_613
	s_mov_b32 s22, 1
	s_mov_b64 s[10:11], 0
	v_mov_b32_e32 v1, 0
	s_branch .LBB0_604

.Lbd_normal_0:
	s_waitcnt lgkmcnt(0)
	buffer_inv sc1
	v_mov_b32_e32 v1, 0x3500
	global_load_dword v1, v1, s[92:93] sc1
	s_add_u32 s10, s92, 0x3500
	s_addc_u32 s11, s93, 0
	s_waitcnt vmcnt(0)
	v_cmp_eq_u32_e32 vcc, v1, v2
	s_and_saveexec_b64 s[8:9], vcc
	s_cbranch_execz .LBB0_679
	s_mov_b32 s22, 1
	s_mov_b64 s[12:13], 0
	v_mov_b32_e32 v1, 0
	s_branch .LBB0_670

.LBB0_781:
	s_cmp_eq_u32 s99, 1
	s_cbranch_scc0 .Lbd_done_0
	s_mov_b32 s99, 0
	s_mov_b64 s[0:1], exec
	v_readlane_b32 s4, v197, 0
	v_readlane_b32 s5, v197, 1
	s_and_b64 s[4:5], s[0:1], s[4:5]
	s_mov_b64 exec, s[4:5]
	s_cbranch_execz .Lbd_rest_0
	v_readlane_b32 s4, v197, 50
	s_lshl_b32 s4, s4, 8
	s_add_u32 s4, s92, s4
	s_addc_u32 s5, s93, 0
	s_add_u32 s4, s92, 0x3500
	s_addc_u32 s5, s93, 0
	v_mov_b32_e32 v1, 0
	v_mov_b32_e32 v2, s98

.LBB0_860:
	s_or_b64 exec, exec, s[6:7]
	v_cvt_f32_u32_e32 v5, v3
	s_waitcnt vmcnt(0)
	v_readfirstlane_b32 s4, v4
	v_sub_u32_e32 v4, 0, v3
	v_rcp_iflag_f32_e32 v5, v5
	v_add_u32_e32 v6, s4, v2
	v_mul_f32_e32 v5, 0x4f7ffffe, v5
	v_cvt_u32_f32_e32 v5, v5
	v_mul_lo_u32 v2, v4, v5
	v_mul_hi_u32 v2, v5, v2
	v_add_u32_e32 v2, v5, v2
	v_mul_hi_u32 v2, v6, v2
	v_mul_lo_u32 v4, v2, v3
	v_sub_u32_e32 v4, v6, v4
	v_add_u32_e32 v5, 1, v2
	v_cmp_ge_u32_e32 vcc, v4, v3
	s_nop 1
	v_cndmask_b32_e32 v2, v2, v5, vcc
	v_sub_u32_e32 v5, v4, v3
	v_cndmask_b32_e32 v4, v4, v5, vcc
	v_add_u32_e32 v5, 1, v2
	v_cmp_ge_u32_e32 vcc, v4, v3
	v_add_u32_e32 v4, 1, v6
	s_nop 0
	v_cndmask_b32_e32 v2, v2, v5, vcc
	v_mul_lo_u32 v5, v3, v2
	v_add_u32_e32 v3, v5, v3
	v_cmp_ne_u32_e32 vcc, v4, v3
	s_and_saveexec_b64 s[4:5], vcc
	s_xor_b64 s[4:5], exec, s[4:5]
	s_cbranch_execz .LBB0_874
	s_waitcnt lgkmcnt(0)
	buffer_inv sc1
	v_mov_b32_e32 v1, 0x3500
	global_load_dword v1, v1, s[92:93] sc1
	s_add_u32 s8, s92, 0x3500
	s_addc_u32 s9, s93, 0
	s_waitcnt vmcnt(0)
	v_cmp_eq_u32_e32 vcc, v1, v2
	s_and_saveexec_b64 s[6:7], vcc
	s_cbranch_execz .LBB0_873
	s_mov_b32 s20, 1
	s_mov_b64 s[10:11], 0
	v_mov_b32_e32 v1, 0
	s_branch .LBB0_864

.LBB0_919:
	s_or_b64 exec, exec, s[8:9]
	v_cvt_f32_u32_e32 v5, v3
	s_waitcnt vmcnt(0)
	v_readfirstlane_b32 s4, v4
	v_sub_u32_e32 v4, 0, v3
	v_rcp_iflag_f32_e32 v5, v5
	v_add_u32_e32 v6, s4, v2
	v_mul_f32_e32 v5, 0x4f7ffffe, v5
	v_cvt_u32_f32_e32 v5, v5
	v_mul_lo_u32 v2, v4, v5
	v_mul_hi_u32 v2, v5, v2
	v_add_u32_e32 v2, v5, v2
	v_mul_hi_u32 v2, v6, v2
	v_mul_lo_u32 v4, v2, v3
	v_sub_u32_e32 v4, v6, v4
	v_add_u32_e32 v5, 1, v2
	v_cmp_ge_u32_e32 vcc, v4, v3
	s_nop 1
	v_cndmask_b32_e32 v2, v2, v5, vcc
	v_sub_u32_e32 v5, v4, v3
	v_cndmask_b32_e32 v4, v4, v5, vcc
	v_add_u32_e32 v5, 1, v2
	v_cmp_ge_u32_e32 vcc, v4, v3
	v_add_u32_e32 v4, 1, v6
	s_nop 0
	v_cndmask_b32_e32 v2, v2, v5, vcc
	v_mul_lo_u32 v5, v3, v2
	v_add_u32_e32 v3, v5, v3
	v_cmp_ne_u32_e32 vcc, v4, v3
	s_and_saveexec_b64 s[4:5], vcc
	s_xor_b64 s[4:5], exec, s[4:5]
	s_cbranch_execz .LBB0_933
	s_waitcnt lgkmcnt(0)
	buffer_inv sc1
	v_mov_b32_e32 v1, 0x3500
	global_load_dword v1, v1, s[92:93] sc1
	s_add_u32 s10, s92, 0x3500
	s_addc_u32 s11, s93, 0
	s_waitcnt vmcnt(0)
	v_cmp_eq_u32_e32 vcc, v1, v2
	s_and_saveexec_b64 s[8:9], vcc
	s_cbranch_execz .LBB0_932
	s_mov_b32 s22, 1
	s_mov_b64 s[12:13], 0
	v_mov_b32_e32 v1, 0
	s_branch .LBB0_923

.Lbd_normal_1:
	s_waitcnt lgkmcnt(0)
	buffer_inv sc1
	v_mov_b32_e32 v1, 0x3500
	global_load_dword v1, v1, s[92:93] sc1
	s_add_u32 s8, s92, 0x3500
	s_addc_u32 s9, s93, 0
	s_waitcnt vmcnt(0)
	v_cmp_eq_u32_e32 vcc, v1, v2
	s_and_saveexec_b64 s[6:7], vcc
	s_cbranch_execz .LBB0_1268
	s_mov_b32 s20, 1
	s_mov_b64 s[10:11], 0
	v_mov_b32_e32 v1, 0
	s_branch .LBB0_1259

.LBB0_1378:
	s_cmp_eq_u32 s99, 1
	s_cbranch_scc0 .Lbd_done_1
	s_mov_b32 s99, 0
	s_mov_b64 s[0:1], exec
	v_readlane_b32 s2, v197, 0
	v_readlane_b32 s3, v197, 1
	s_and_b64 s[2:3], s[0:1], s[2:3]
	s_mov_b64 exec, s[2:3]
	s_cbranch_execz .Lbd_rest_1
	v_readlane_b32 s2, v197, 50
	s_lshl_b32 s2, s2, 8
	s_add_u32 s2, s92, s2
	s_addc_u32 s3, s93, 0
	s_add_u32 s2, s92, 0x3500
	s_addc_u32 s3, s93, 0
	v_mov_b32_e32 v1, 0
	v_mov_b32_e32 v2, s98
